# WD2: out-proj weight transpose and compress-MLP weight transpose (both layers) also moved from the prologue into the slack of layer 0's in-proj phase, hand-written
# baseline (speedup 1.0000x reference)
.LBB0_97:
	s_or_b64 exec, exec, s[14:15]
	s_mov_b64 s[0:1], 0
	v_cmp_gt_i64_e32 vcc, s[0:1], v[4:5]
	s_and_saveexec_b64 s[0:1], vcc
	v_readlane_b32 s16, v234, 20
	v_readlane_b32 s28, v234, 32
	v_readlane_b32 s29, v234, 33
	v_readlane_b32 s17, v234, 21
	v_readlane_b32 s18, v234, 22
	v_readlane_b32 s19, v234, 23
	v_readlane_b32 s20, v234, 24
	v_readlane_b32 s21, v234, 25
	v_readlane_b32 s22, v234, 26
	v_readlane_b32 s23, v234, 27
	v_readlane_b32 s24, v234, 28
	v_readlane_b32 s25, v234, 29
	v_readlane_b32 s26, v234, 30
	v_readlane_b32 s27, v234, 31
	v_readlane_b32 s30, v234, 34
	v_readlane_b32 s31, v234, 35
	s_cbranch_execz .LBB0_100
	s_add_u32 s6, s80, 0x1400000
	s_addc_u32 s7, s81, 0
	s_lshl_b64 s[14:15], s[74:75], 23
	v_lshlrev_b64 v[0:1], 15, v[6:7]
	v_lshl_add_u64 v[0:1], s[14:15], 0, v[0:1]
	s_lshl_b64 s[14:15], s[60:61], 23
	s_mov_b64 s[16:17], 0
	s_waitcnt lgkmcnt(0)
	v_mov_b32_e32 v3, 0
	s_movk_i32 s20, 0x2000
	s_movk_i32 s21, 0x4000
	s_movk_i32 s22, 0x6000
	s_movk_i32 s23, 0x7000
	s_mov_b64 s[18:19], 0x3ffff
	v_mov_b64_e32 v[8:9], v[4:5]

.LBB0_100:
	s_or_b64 exec, exec, s[0:1]
	s_mov_b64 s[0:1], 0
	v_cmp_gt_i64_e32 vcc, s[0:1], v[4:5]
	s_and_saveexec_b64 s[0:1], vcc
	s_cbranch_execz .LBB0_103
	v_readlane_b32 s44, v234, 2
	v_readlane_b32 s48, v234, 6
	v_readlane_b32 s49, v234, 7
	v_readlane_b32 s50, v234, 8
	v_readlane_b32 s51, v234, 9
	v_readlane_b32 s56, v234, 14
	v_readlane_b32 s57, v234, 15
	s_add_u32 s6, s80, 0x1800000
	v_readlane_b32 s46, v234, 4
	v_readlane_b32 s47, v234, 5
	v_readlane_b32 s54, v234, 12
	v_readlane_b32 s55, v234, 13
	v_readlane_b32 s58, v234, 16
	v_readlane_b32 s59, v234, 17
	s_mov_b64 s[48:49], s[56:57]
	s_addc_u32 s7, s81, 0
	v_and_b32_e32 v0, 0x7f, v6
	s_waitcnt lgkmcnt(0)
	v_mov_b32_e32 v3, 0
	s_lshl_b64 s[14:15], s[74:75], 24
	v_lshlrev_b64 v[8:9], 16, v[6:7]
	s_mov_b64 s[46:47], s[54:55]
	s_mov_b64 s[50:51], s[58:59]
	v_lshl_add_u64 v[8:9], s[14:15], 0, v[8:9]
	s_lshl_b64 s[14:15], s[60:61], 24
	s_mov_b64 s[16:17], 0
	v_mov_b32_e32 v1, s51
	v_mov_b32_e32 v14, s47
	v_mov_b32_e32 v15, s50
	v_mov_b32_e32 v16, s46
	v_lshlrev_b32_e32 v10, 2, v0
	v_mov_b32_e32 v11, v3
	s_mov_b64 s[18:19], 0x1ffff
	v_mov_b64_e32 v[12:13], v[4:5]
	v_readlane_b32 s45, v234, 3
	v_readlane_b32 s52, v234, 10
	v_readlane_b32 s53, v234, 11

.Lwd_done:
	v_readlane_b32 s12, v234, 32
	v_readlane_b32 s13, v234, 33
	s_add_u32 s0, s80, 0x1400000
	s_addc_u32 s1, s81, 0
	s_lshl_b32 s6, s5, 8
	v_add_u32_e32 v18, s6, v156
	s_mov_b32 s4, 0
.Lwd2_oloop:
	v_lshrrev_b32_e32 v19, 6, v18
	v_and_b32_e32 v2, 31, v19
	v_bfe_u32 v3, v18, 3, 3
	v_lshl_or_b32 v2, v2, 3, v3
	v_lshrrev_b32_e32 v3, 5, v19
	v_and_b32_e32 v8, 7, v18
	v_lshl_or_b32 v3, v3, 3, v8
	v_lshlrev_b32_e32 v14, 15, v3
	v_lshl_or_b32 v14, v2, 4, v14
	v_lshrrev_b32_e32 v8, 7, v3
	v_lshlrev_b32_e32 v15, 21, v8
	v_lshl_or_b32 v15, v2, 13, v15
	v_and_b32_e32 v8, 0x7f, v3
	v_lshl_or_b32 v15, v8, 4, v15
	v_add_u32_e32 v16, 0x1000, v15
	global_load_dwordx4 v[20:23], v14, s[12:13]
	v_add_u32_e32 v14, 0x1000, v14
	global_load_dwordx4 v[24:27], v14, s[12:13]
	v_add_u32_e32 v14, 0x1000, v14
	global_load_dwordx4 v[28:31], v14, s[12:13]
	v_add_u32_e32 v14, 0x1000, v14
	global_load_dwordx4 v[32:35], v14, s[12:13]
	v_add_u32_e32 v14, 0x1000, v14
	global_load_dwordx4 v[36:39], v14, s[12:13]
	v_add_u32_e32 v14, 0x1000, v14
	global_load_dwordx4 v[40:43], v14, s[12:13]
	v_add_u32_e32 v14, 0x1000, v14
	global_load_dwordx4 v[44:47], v14, s[12:13]
	v_add_u32_e32 v14, 0x1000, v14
	global_load_dwordx4 v[48:51], v14, s[12:13]
	v_add_u32_e32 v11, 0x4000, v18
	v_lshrrev_b32_e32 v19, 6, v11
	v_and_b32_e32 v2, 31, v19
	v_bfe_u32 v3, v11, 3, 3
	v_lshl_or_b32 v2, v2, 3, v3
	v_lshrrev_b32_e32 v3, 5, v19
	v_and_b32_e32 v8, 7, v11
	v_lshl_or_b32 v3, v3, 3, v8
	v_lshlrev_b32_e32 v104, 15, v3
	v_lshl_or_b32 v104, v2, 4, v104
	v_lshrrev_b32_e32 v8, 7, v3
	v_lshlrev_b32_e32 v105, 21, v8
	v_lshl_or_b32 v105, v2, 13, v105
	v_and_b32_e32 v8, 0x7f, v3
	v_lshl_or_b32 v105, v8, 4, v105
	v_add_u32_e32 v106, 0x1000, v105
	global_load_dwordx4 v[52:55], v104, s[12:13]
	v_add_u32_e32 v104, 0x1000, v104
	global_load_dwordx4 v[56:59], v104, s[12:13]
	v_add_u32_e32 v104, 0x1000, v104
	global_load_dwordx4 v[60:63], v104, s[12:13]
	v_add_u32_e32 v104, 0x1000, v104
	global_load_dwordx4 v[64:67], v104, s[12:13]
	v_add_u32_e32 v104, 0x1000, v104
	global_load_dwordx4 v[68:71], v104, s[12:13]
	v_add_u32_e32 v104, 0x1000, v104
	global_load_dwordx4 v[72:75], v104, s[12:13]
	v_add_u32_e32 v104, 0x1000, v104
	global_load_dwordx4 v[76:79], v104, s[12:13]
	v_add_u32_e32 v104, 0x1000, v104
	global_load_dwordx4 v[80:83], v104, s[12:13]
	s_waitcnt vmcnt(8)
	v_cvt_pk_bf16_f32 v84, v20, v24
	v_cvt_pk_bf16_f32 v85, v28, v32
	v_cvt_pk_bf16_f32 v86, v36, v40
	v_cvt_pk_bf16_f32 v87, v44, v48
	v_cvt_pk_bf16_f32 v88, v21, v25
	v_cvt_pk_bf16_f32 v89, v29, v33
	v_cvt_pk_bf16_f32 v90, v37, v41
	v_cvt_pk_bf16_f32 v91, v45, v49
	v_cvt_pk_bf16_f32 v92, v22, v26
	v_cvt_pk_bf16_f32 v93, v30, v34
	v_cvt_pk_bf16_f32 v94, v38, v42
	v_cvt_pk_bf16_f32 v95, v46, v50
	v_cvt_pk_bf16_f32 v96, v23, v27
	v_cvt_pk_bf16_f32 v97, v31, v35
	v_cvt_pk_bf16_f32 v98, v39, v43
	v_cvt_pk_bf16_f32 v99, v47, v51
	global_store_dwordx4 v15, v[84:87], s[0:1]
	global_store_dwordx4 v15, v[88:91], s[0:1] offset:2048
	global_store_dwordx4 v16, v[92:95], s[0:1]
	global_store_dwordx4 v16, v[96:99], s[0:1] offset:2048
	s_waitcnt vmcnt(4)
	s_nop 0
	v_cvt_pk_bf16_f32 v84, v52, v56
	v_cvt_pk_bf16_f32 v85, v60, v64
	v_cvt_pk_bf16_f32 v86, v68, v72
	v_cvt_pk_bf16_f32 v87, v76, v80
	v_cvt_pk_bf16_f32 v88, v53, v57
	v_cvt_pk_bf16_f32 v89, v61, v65
	v_cvt_pk_bf16_f32 v90, v69, v73
	v_cvt_pk_bf16_f32 v91, v77, v81
	v_cvt_pk_bf16_f32 v92, v54, v58
	v_cvt_pk_bf16_f32 v93, v62, v66
	v_cvt_pk_bf16_f32 v94, v70, v74
	v_cvt_pk_bf16_f32 v95, v78, v82
	v_cvt_pk_bf16_f32 v96, v55, v59
	v_cvt_pk_bf16_f32 v97, v63, v67
	v_cvt_pk_bf16_f32 v98, v71, v75
	v_cvt_pk_bf16_f32 v99, v79, v83
	global_store_dwordx4 v105, v[84:87], s[0:1]
	global_store_dwordx4 v105, v[88:91], s[0:1] offset:2048
	global_store_dwordx4 v106, v[92:95], s[0:1]
	global_store_dwordx4 v106, v[96:99], s[0:1] offset:2048
	v_add_u32_e32 v18, 0x8000, v18
	s_add_u32 s4, s4, 1
	s_cmp_lt_u32 s4, 2
	s_cbranch_scc1 .Lwd2_oloop
	v_readlane_b32 s12, v234, 12
	v_readlane_b32 s13, v234, 13
	v_readlane_b32 s6, v234, 16
	v_readlane_b32 s7, v234, 17
	s_add_u32 s0, s80, 0x1800000
	s_addc_u32 s1, s81, 0
	s_lshl_b32 s8, s5, 8
	v_add_u32_e32 v18, s8, v156
	v_mov_b32_e32 v108, s12
	v_mov_b32_e32 v109, s13
	v_mov_b32_e32 v110, s6
	v_mov_b32_e32 v111, s7
	v_lshrrev_b32_e32 v19, 6, v18
	v_lshrrev_b32_e32 v2, 2, v19
	v_and_b32_e32 v3, 3, v19
	v_bfe_u32 v8, v18, 3, 3
	v_lshl_or_b32 v3, v3, 3, v8
	v_and_b32_e32 v8, 31, v2
	v_and_b32_e32 v9, 7, v18
	v_lshl_or_b32 v8, v8, 3, v9
	v_lshrrev_b32_e32 v9, 5, v2
	v_lshrrev_b32_e32 v10, 1, v9
	v_lshlrev_b32_e32 v12, 20, v10
	v_lshl_or_b32 v12, v8, 12, v12
	v_lshl_or_b32 v12, v3, 4, v12
	v_mov_b32_e32 v13, 0
	v_and_b32_e32 v10, 1, v9
	v_cmp_eq_u32_e32 vcc, 1, v10
	s_nop 1
	v_cndmask_b32_e32 v14, v108, v110, vcc
	v_cndmask_b32_e32 v15, v109, v111, vcc
	v_lshl_add_u64 v[14:15], v[14:15], 0, v[12:13]
	v_lshlrev_b32_e32 v16, 19, v9
	v_lshl_or_b32 v16, v3, 14, v16
	v_lshl_or_b32 v16, v8, 4, v16
	global_load_dwordx4 v[20:23], v[14:15], off
	global_load_dwordx4 v[24:27], v[14:15], off offset:512
	global_load_dwordx4 v[28:31], v[14:15], off offset:1024
	global_load_dwordx4 v[32:35], v[14:15], off offset:1536
	global_load_dwordx4 v[36:39], v[14:15], off offset:2048
	global_load_dwordx4 v[40:43], v[14:15], off offset:2560
	global_load_dwordx4 v[44:47], v[14:15], off offset:3072
	global_load_dwordx4 v[48:51], v[14:15], off offset:3584
	v_add_u32_e32 v11, 0x4000, v18
	v_lshrrev_b32_e32 v19, 6, v11
	v_lshrrev_b32_e32 v2, 2, v19
	v_and_b32_e32 v3, 3, v19
	v_bfe_u32 v8, v11, 3, 3
	v_lshl_or_b32 v3, v3, 3, v8
	v_and_b32_e32 v8, 31, v2
	v_and_b32_e32 v9, 7, v11
	v_lshl_or_b32 v8, v8, 3, v9
	v_lshrrev_b32_e32 v9, 5, v2
	v_lshrrev_b32_e32 v10, 1, v9
	v_lshlrev_b32_e32 v12, 20, v10
	v_lshl_or_b32 v12, v8, 12, v12
	v_lshl_or_b32 v12, v3, 4, v12
	v_mov_b32_e32 v13, 0
	v_and_b32_e32 v10, 1, v9
	v_cmp_eq_u32_e32 vcc, 1, v10
	s_nop 1
	v_cndmask_b32_e32 v104, v108, v110, vcc
	v_cndmask_b32_e32 v105, v109, v111, vcc
	v_lshl_add_u64 v[104:105], v[104:105], 0, v[12:13]
	v_lshlrev_b32_e32 v106, 19, v9
	v_lshl_or_b32 v106, v3, 14, v106
	v_lshl_or_b32 v106, v8, 4, v106
	global_load_dwordx4 v[52:55], v[104:105], off
	global_load_dwordx4 v[56:59], v[104:105], off offset:512
	global_load_dwordx4 v[60:63], v[104:105], off offset:1024
	global_load_dwordx4 v[64:67], v[104:105], off offset:1536
	global_load_dwordx4 v[68:71], v[104:105], off offset:2048
	global_load_dwordx4 v[72:75], v[104:105], off offset:2560
	global_load_dwordx4 v[76:79], v[104:105], off offset:3072
	global_load_dwordx4 v[80:83], v[104:105], off offset:3584
	s_waitcnt vmcnt(8)
	v_cvt_pk_bf16_f32 v84, v20, v24
	v_cvt_pk_bf16_f32 v85, v28, v32
	v_cvt_pk_bf16_f32 v86, v36, v40
	v_cvt_pk_bf16_f32 v87, v44, v48
	v_cvt_pk_bf16_f32 v88, v21, v25
	v_cvt_pk_bf16_f32 v89, v29, v33
	v_cvt_pk_bf16_f32 v90, v37, v41
	v_cvt_pk_bf16_f32 v91, v45, v49
	v_cvt_pk_bf16_f32 v92, v22, v26
	v_cvt_pk_bf16_f32 v93, v30, v34
	v_cvt_pk_bf16_f32 v94, v38, v42
	v_cvt_pk_bf16_f32 v95, v46, v50
	v_cvt_pk_bf16_f32 v96, v23, v27
	v_cvt_pk_bf16_f32 v97, v31, v35
	v_cvt_pk_bf16_f32 v98, v39, v43
	v_cvt_pk_bf16_f32 v99, v47, v51
	global_store_dwordx4 v16, v[84:87], s[0:1]
	v_add_u32_e32 v16, 0x1000, v16
	global_store_dwordx4 v16, v[88:91], s[0:1]
	v_add_u32_e32 v16, 0x1000, v16
	global_store_dwordx4 v16, v[92:95], s[0:1]
	v_add_u32_e32 v16, 0x1000, v16
	global_store_dwordx4 v16, v[96:99], s[0:1]
	s_waitcnt vmcnt(4)
	s_nop 0
	v_cvt_pk_bf16_f32 v84, v52, v56
	v_cvt_pk_bf16_f32 v85, v60, v64
	v_cvt_pk_bf16_f32 v86, v68, v72
	v_cvt_pk_bf16_f32 v87, v76, v80
	v_cvt_pk_bf16_f32 v88, v53, v57
	v_cvt_pk_bf16_f32 v89, v61, v65
	v_cvt_pk_bf16_f32 v90, v69, v73
	v_cvt_pk_bf16_f32 v91, v77, v81
	v_cvt_pk_bf16_f32 v92, v54, v58
	v_cvt_pk_bf16_f32 v93, v62, v66
	v_cvt_pk_bf16_f32 v94, v70, v74
	v_cvt_pk_bf16_f32 v95, v78, v82
	v_cvt_pk_bf16_f32 v96, v55, v59
	v_cvt_pk_bf16_f32 v97, v63, v67
	v_cvt_pk_bf16_f32 v98, v71, v75
	v_cvt_pk_bf16_f32 v99, v79, v83
	global_store_dwordx4 v106, v[84:87], s[0:1]
	v_add_u32_e32 v106, 0x1000, v106
	global_store_dwordx4 v106, v[88:91], s[0:1]
	v_add_u32_e32 v106, 0x1000, v106
	global_store_dwordx4 v106, v[92:95], s[0:1]
	v_add_u32_e32 v106, 0x1000, v106
	global_store_dwordx4 v106, v[96:99], s[0:1]
